# up GEMM: per-lane address VGPRs kept alive across units (epilogue registers renamed); units after the first take a VALU-free prologue with SGPR-base LDS-DMA pieces
# speedup vs baseline: 1.0034x; 1.0012x over previous
.LBB0_156:
	s_ashr_i32 s8, s29, 3
	s_add_i32 s8, s30, s8
	s_mul_hi_i32 s9, s8, 0x2e8ba2e9
	s_lshr_b32 s28, s9, 31
	s_ashr_i32 s9, s9, 5
	s_add_i32 s9, s9, s28
	s_lshl_b32 s28, s9, 3
	v_readlane_b32 s29, v255, 20
	s_sub_i32 s29, s29, s28
	s_min_i32 s29, s29, 8
	s_abs_i32 s30, s29
	v_cvt_f32_u32_e32 v2, s30
	s_sub_i32 s39, 0, s30
	s_mulk_i32 s9, 0xb0
	s_sub_i32 s9, s8, s9
	v_rcp_iflag_f32_e32 v2, v2
	s_abs_i32 s8, s9
	s_xor_b32 s38, s9, s29
	s_ashr_i32 s38, s38, 31
	v_mul_f32_e32 v2, 0x4f7ffffe, v2
	v_cvt_u32_f32_e32 v2, v2
	s_nop 0
	v_readfirstlane_b32 s40, v2
	s_mul_i32 s39, s39, s40
	s_mul_hi_u32 s39, s40, s39
	s_add_i32 s40, s40, s39
	s_mul_hi_u32 s39, s8, s40
	s_mul_i32 s40, s39, s30
	s_sub_i32 s8, s8, s40
	s_add_i32 s44, s39, 1
	s_sub_i32 s40, s8, s30
	s_cmp_ge_u32 s8, s30
	s_cselect_b32 s39, s44, s39
	s_cselect_b32 s8, s40, s8
	s_add_i32 s40, s39, 1
	s_cmp_ge_u32 s8, s30
	s_cselect_b32 s8, s40, s39
	s_xor_b32 s8, s8, s38
	s_sub_i32 s8, s8, s38
	s_mul_i32 s29, s8, s29
	s_sub_i32 s9, s9, s29
	s_add_i32 s30, s28, s9
	s_andn2_b64 vcc, exec, s[6:7]
	s_mov_b64 s[6:7], -1
	s_cbranch_vccnz .LBB0_149
.LBB0_157:
	s_cmp_lg_u32 s48, 0
	s_cbranch_scc1 .Lup_lite
	v_mov_b32_e32 v16, v191
	v_mov_b32_e32 v7, 1
	v_ashrrev_i32_e32 v0, 31, v16
	v_lshrrev_b32_e32 v0, 26, v0
	v_add_u32_e32 v0, v16, v0
	v_ashrrev_i32_e32 v10, 6, v0
	v_bfe_i32 v0, v16, 27, 1
	v_lshlrev_b32_e32 v2, 4, v16
	v_lshrrev_b32_e32 v0, 22, v0
	v_add_u32_e32 v0, v2, v0
	v_and_b32_e32 v0, 0xfffffc00, v0
	v_sub_u32_e32 v0, v2, v0
	v_lshrrev_b32_e32 v3, 4, v0
	v_bitop3_b32 v3, v3, v0, 32 bitop3:0x6c
	v_ashrrev_i32_e32 v0, 31, v0
	v_lshrrev_b32_e32 v0, 26, v0
	v_add_u32_e32 v0, v3, v0
	v_ashrrev_i32_e32 v11, 6, v0
	v_lshlrev_b32_e32 v4, 3, v10
	v_mul_i32_i24_e32 v5, 64, v11
	v_and_b32_e32 v4, -16, v4
	v_sub_u32_e32 v3, v3, v5
	v_add_u32_e32 v0, v11, v4
	v_ashrrev_i16_sdwa v3, v7, sext(v3) dst_sel:DWORD dst_unused:UNUSED_PAD src0_sel:DWORD src1_sel:BYTE_0
	v_lshlrev_b32_e32 v4, 5, v10
	v_bfe_i32 v12, v3, 0, 16
	v_lshlrev_b32_e32 v3, 1, v0
	v_lshrrev_b32_e32 v5, 2, v0
	v_and_b32_e32 v6, 3, v11
	s_mov_b32 s6, 0x1fffe0
	v_and_b32_e32 v4, 32, v4
	v_and_b32_e32 v3, 24, v3
	v_and_b32_e32 v5, 4, v5
	v_and_or_b32 v6, v0, s6, v6
	v_or3_b32 v3, v6, v5, v3
	v_add_lshl_u32 v4, v4, v12, 1
	v_add_u32_e32 v2, 0x2000, v2
	v_lshl_add_u32 v130, v0, 11, v4
	v_lshl_add_u32 v0, v3, 11, v4
	v_ashrrev_i32_e32 v3, 31, v2
	v_lshrrev_b32_e32 v3, 22, v3
	v_add_u32_e32 v3, v2, v3
	v_ashrrev_i32_e32 v13, 10, v3
	v_mul_i32_i24_e32 v3, 0x400, v13
	v_sub_u32_e32 v2, v2, v3
	v_lshrrev_b32_e32 v3, 4, v2
	v_bitop3_b32 v2, v3, v2, 32 bitop3:0x6c
	v_ashrrev_i32_e32 v4, 31, v2
	v_lshrrev_b32_e32 v4, 26, v4
	v_readfirstlane_b32 s40, v16
	v_lshlrev_b32_e32 v3, 3, v13
	v_add_u32_e32 v4, v2, v4
	s_ashr_i32 s44, s40, 6
	v_and_b32_e32 v3, -16, v3
	v_ashrrev_i32_e32 v14, 6, v4
	s_ashr_i32 s9, s8, 31
	v_add_u32_e32 v3, v14, v3
	v_and_b32_e32 v6, 3, v14
	s_ashr_i32 s59, s40, 8
	s_lshl_b32 s49, s44, 10
	s_lshl_b64 s[38:39], s[8:9], 19
	v_and_b32_e32 v4, 0xc0, v4
	v_and_or_b32 v6, v3, s6, v6
	s_add_u32 s6, s5, s38
	v_sub_u32_e32 v2, v2, v4
	s_addc_u32 s7, s31, s39
	s_add_i32 s9, s49, 0
	v_ashrrev_i16_sdwa v2, v7, sext(v2) dst_sel:DWORD dst_unused:UNUSED_PAD src0_sel:DWORD src1_sel:BYTE_0
	s_add_i32 m0, s9, 0x10000
	v_lshlrev_b32_e32 v5, 5, v13
	v_bfe_i32 v15, v2, 0, 16
	v_lshlrev_b32_e32 v2, 1, v3
	v_lshrrev_b32_e32 v4, 2, v3
	s_mul_i32 s58, s30, 0x7f000
	global_load_lds_dwordx4 v0, s[6:7]
	s_add_i32 m0, s9, 0x12000
	v_and_b32_e32 v5, 32, v5
	v_and_b32_e32 v2, 24, v2
	v_and_b32_e32 v4, 4, v4
	s_mul_hi_i32 s45, s30, 0x7f000
	s_add_u32 s28, s3, s58
	v_or3_b32 v2, v6, v4, v2
	v_add_lshl_u32 v4, v5, v15, 1
	s_addc_u32 s29, s4, s45
	v_lshl_add_u32 v134, v2, 11, v4
	s_add_u32 s56, s6, 0x40000
	global_load_lds_dwordx4 v134, s[6:7]
	s_addc_u32 s57, s7, 0
	s_add_i32 m0, s9, 0x14000
	v_lshl_add_u32 v132, v3, 11, v4
	global_load_lds_dwordx4 v0, s[56:57]
	s_add_i32 m0, s9, 0x16000
	v_mov_b32_e32 v135, v1
	global_load_lds_dwordx4 v134, s[56:57]
	s_add_i32 s56, s9, 0x2000
	s_mov_b32 m0, s9
	s_add_u32 s70, s28, 0x40000
	global_load_lds_dwordx4 v130, s[28:29]
	s_mov_b32 m0, s56
	s_addc_u32 s71, s29, 0
	s_add_i32 s57, s9, 0x4000
	global_load_lds_dwordx4 v132, s[28:29]
	s_mov_b32 m0, s57
	s_add_i32 s66, s9, 0x6000
	global_load_lds_dwordx4 v130, s[70:71]
	s_mov_b32 m0, s66
	v_mov_b32_e32 v131, v1
	global_load_lds_dwordx4 v132, s[70:71]
	v_mov_b32_e32 v133, v1
	v_lshl_add_u64 v[8:9], s[6:7], 0, v[0:1]
	v_lshl_add_u64 v[6:7], s[6:7], 0, v[134:135]
	v_lshl_add_u64 v[4:5], s[28:29], 0, v[130:131]
	s_cmp_lg_u32 s59, 1
	v_lshl_add_u64 v[2:3], s[28:29], 0, v[132:133]
	s_cbranch_scc1 .LBB0_159
	s_barrier
.LBB0_159:
	s_and_b32 s67, s44, 3
	v_and_b32_e32 v17, 48, v16
	v_lshlrev_b32_e32 v18, 6, v16
	s_movk_i32 s44, 0x3c0
	s_add_i32 m0, s9, 0x18000
	v_lshl_add_u64 v[8:9], v[8:9], 0, s[86:87]
	s_lshl_b32 s70, s59, 6
	v_and_or_b32 v17, v18, s44, v17
	s_lshl_b32 s44, s59, 13
	s_lshl_b32 s59, s67, 12
	s_waitcnt vmcnt(2)
	s_barrier
	global_load_lds_dwordx4 v[8:9], off
	v_lshl_add_u64 v[6:7], v[6:7], 0, s[86:87]
	s_add_i32 m0, s9, 0x1a000
	s_add_i32 s71, s9, 0x8000
	s_add_i32 s74, s9, 0xa000
	global_load_lds_dwordx4 v[6:7], off
	v_lshl_add_u64 v[4:5], v[4:5], 0, s[86:87]
	s_mov_b32 m0, s71
	s_add_u32 s76, s6, 0x40080
	global_load_lds_dwordx4 v[4:5], off
	v_lshl_add_u64 v[2:3], v[2:3], 0, s[86:87]
	s_mov_b32 m0, s74
	s_addc_u32 s77, s7, 0
	global_load_lds_dwordx4 v[2:3], off
	s_add_i32 m0, s9, 0x1c000
	v_lshl_add_u64 v[2:3], s[76:77], 0, v[0:1]
	global_load_lds_dwordx4 v[2:3], off
	v_lshl_add_u64 v[2:3], s[76:77], 0, v[134:135]
	s_add_i32 m0, s9, 0x1e000
	v_lshlrev_b32_e32 v16, 2, v16
	global_load_lds_dwordx4 v[2:3], off
	s_waitcnt vmcnt(6)
	s_barrier
	s_load_dwordx2 s[76:77], s[0:1], 0xc8
	v_lshlrev_b32_e32 v2, 14, v10
	v_and_b32_e32 v2, 0xffff8000, v2
	v_and_b32_e32 v16, 32, v16
	v_lshl_add_u32 v2, v11, 11, v2
	s_waitcnt lgkmcnt(0)
	s_add_u32 s76, s76, s58
	s_addc_u32 s77, s77, s45
	v_and_b32_e32 v3, 1, v10
	v_bitop3_b32 v18, v17, s44, v16 bitop3:0xde
	v_lshl_or_b32 v2, v3, 6, v2
	s_add_u32 s44, s33, s58
	v_lshl_add_u32 v2, v12, 1, v2
	v_mov_b32_e32 v3, v1
	s_addc_u32 s45, s42, s45
	v_add_u32_e32 v136, 0, v2
	v_lshlrev_b32_e32 v2, 14, v13
	v_and_b32_e32 v2, 0xffff8000, v2
	v_lshl_add_u32 v2, v14, 11, v2
	v_and_b32_e32 v3, 1, v13
	v_lshl_or_b32 v2, v3, 6, v2
	v_lshl_add_u32 v2, v15, 1, v2
	v_mov_b32_e32 v3, v1
	v_add_u32_e32 v138, 0, v2
	s_add_u32 s78, s43, s38
	v_bitop3_b32 v140, v17, s59, v16 bitop3:0xde
	s_addc_u32 s79, s46, s39
	s_mov_b32 s81, -2
	s_mov_b64 s[38:39], 0
	v_add_u32_e32 v141, 0, v18
	s_branch .Lup_join2
.Lup_lite:
	v_readfirstlane_b32 s40, v191
	s_mov_b32 s6, 0x1fffe0
	s_ashr_i32 s44, s40, 6
	s_ashr_i32 s9, s8, 31
	s_ashr_i32 s59, s40, 8
	s_lshl_b32 s49, s44, 10
	s_lshl_b64 s[38:39], s[8:9], 19
	s_add_u32 s6, s5, s38
	s_addc_u32 s7, s31, s39
	s_add_i32 s9, s49, 0
	s_add_i32 m0, s9, 0x10000
	s_mul_i32 s58, s30, 0x7f000
	global_load_lds_dwordx4 v0, s[6:7]
	s_add_i32 m0, s9, 0x12000
	s_mul_hi_i32 s45, s30, 0x7f000
	s_add_u32 s28, s3, s58
	s_addc_u32 s29, s4, s45
	s_add_u32 s56, s6, 0x40000
	global_load_lds_dwordx4 v134, s[6:7]
	s_addc_u32 s57, s7, 0
	s_add_i32 m0, s9, 0x14000
	s_nop 0
	global_load_lds_dwordx4 v0, s[56:57]
	s_add_i32 m0, s9, 0x16000
	s_nop 0
	global_load_lds_dwordx4 v134, s[56:57]
	s_add_i32 s56, s9, 0x2000
	s_mov_b32 m0, s9
	s_add_u32 s70, s28, 0x40000
	global_load_lds_dwordx4 v130, s[28:29]
	s_mov_b32 m0, s56
	s_addc_u32 s71, s29, 0
	s_add_i32 s57, s9, 0x4000
	global_load_lds_dwordx4 v132, s[28:29]
	s_mov_b32 m0, s57
	s_add_i32 s66, s9, 0x6000
	global_load_lds_dwordx4 v130, s[70:71]
	s_mov_b32 m0, s66
	s_nop 0
	global_load_lds_dwordx4 v132, s[70:71]
	s_cmp_lg_u32 s59, 1
	s_cbranch_scc1 .Lup_lite_159
	s_barrier
.Lup_lite_159:
	s_and_b32 s67, s44, 3
	s_lshl_b32 s70, s59, 6
	s_lshl_b32 s44, s59, 13
	s_lshl_b32 s59, s67, 12
	s_waitcnt vmcnt(2)
	s_barrier
	s_add_u32 s100, s6, 0x80
	s_addc_u32 s101, s7, 0
	s_add_i32 m0, s9, 0x18000
	s_nop 0
	global_load_lds_dwordx4 v0, s[100:101]
	s_add_i32 m0, s9, 0x1a000
	s_nop 0
	global_load_lds_dwordx4 v134, s[100:101]
	s_add_i32 s71, s9, 0x8000
	s_add_i32 s74, s9, 0xa000
	s_add_u32 s100, s28, 0x80
	s_addc_u32 s101, s29, 0
	s_mov_b32 m0, s71
	s_nop 0
	global_load_lds_dwordx4 v130, s[100:101]
	s_mov_b32 m0, s74
	s_nop 0
	global_load_lds_dwordx4 v132, s[100:101]
	s_add_u32 s100, s6, 0x40080
	s_addc_u32 s101, s7, 0
	s_add_i32 m0, s9, 0x1c000
	s_nop 0
	global_load_lds_dwordx4 v0, s[100:101]
	s_add_i32 m0, s9, 0x1e000
	s_nop 0
	global_load_lds_dwordx4 v134, s[100:101]
	s_waitcnt vmcnt(6)
	s_barrier
	s_load_dwordx2 s[76:77], s[0:1], 0xc8
	s_waitcnt lgkmcnt(0)
	s_add_u32 s76, s76, s58
	s_addc_u32 s77, s77, s45
	s_add_u32 s78, s43, s38
	s_addc_u32 s79, s46, s39
	s_mov_b32 s81, -2
	s_mov_b64 s[38:39], 0
	s_branch .Lup_join2
.Lup_join2:
	s_add_u32 s44, s76, s38
	s_addc_u32 s45, s77, s39
	s_add_u32 s44, s44, 0x3800900
	s_addc_u32 s45, s45, 0
	s_add_u32 s100, s44, 0x3ff80
	s_addc_u32 s101, s45, 0
	s_add_u32 s85, s78, s38
	s_addc_u32 s93, s79, s39
	s_add_i32 vcc_lo, 0, 0x10000
	s_cmpk_eq_i32 s38, 0x700
	s_cselect_b32 s59, s29, s45
	s_cselect_b32 s58, s28, s44
	s_cselect_b32 s45, s7, s93
	s_cselect_b32 s44, s6, s85
	s_add_i32 s85, 0, 0x14000
	v_add_u32_e32 v154, vcc_lo, v140
	v_add_u32_e32 v170, s85, v140
	ds_read_b128 v[142:145], v154
	ds_read_b128 v[146:149], v154 offset:1024
	ds_read_b128 v[150:153], v154 offset:2048
	ds_read_b128 v[154:157], v154 offset:3072
	ds_read_b128 v[158:161], v170
	ds_read_b128 v[162:165], v170 offset:1024
	ds_read_b128 v[166:169], v170 offset:2048
	ds_read_b128 v[170:173], v170 offset:3072
	s_add_i32 m0, s9, 0xc000
	ds_read_b128 v[174:177], v141
	ds_read_b128 v[178:181], v141 offset:1024
	ds_read_b128 v[182:185], v141 offset:2048
	ds_read_b128 v[186:189], v141 offset:3072
	ds_read_b128 v[192:195], v141 offset:4096
	ds_read_b128 v[196:199], v141 offset:5120
	ds_read_b128 v[200:203], v141 offset:6144
	ds_read_b128 v[204:207], v141 offset:7168
	global_load_lds_dwordx4 v136, s[100:101]
	s_add_i32 m0, s9, 0xe000
	s_nop 0
	global_load_lds_dwordx4 v138, s[100:101]
	s_waitcnt vmcnt(8)
	s_waitcnt lgkmcnt(0)
	s_barrier
	s_setprio 1
	s_waitcnt lgkmcnt(0)
	v_mfma_f32_16x16x32_bf16 v[126:129], v[142:145], v[174:177], 0
	v_mfma_f32_16x16x32_bf16 v[122:125], v[150:153], v[174:177], 0
	v_mfma_f32_16x16x32_bf16 v[118:121], v[142:145], v[182:185], 0
	v_mfma_f32_16x16x32_bf16 v[114:117], v[150:153], v[182:185], 0
	v_mfma_f32_16x16x32_bf16 v[102:105], v[142:145], v[192:195], 0
	v_mfma_f32_16x16x32_bf16 v[98:101], v[150:153], v[192:195], 0
	v_mfma_f32_16x16x32_bf16 v[86:89], v[142:145], v[200:203], 0
	v_mfma_f32_16x16x32_bf16 v[82:85], v[150:153], v[200:203], 0
	v_mfma_f32_16x16x32_bf16 v[126:129], v[146:149], v[178:181], v[126:129]
	v_mfma_f32_16x16x32_bf16 v[122:125], v[154:157], v[178:181], v[122:125]
	v_mfma_f32_16x16x32_bf16 v[118:121], v[146:149], v[186:189], v[118:121]
	v_mfma_f32_16x16x32_bf16 v[114:117], v[154:157], v[186:189], v[114:117]
	v_mfma_f32_16x16x32_bf16 v[102:105], v[146:149], v[196:199], v[102:105]
	v_mfma_f32_16x16x32_bf16 v[98:101], v[154:157], v[196:199], v[98:101]
	v_mfma_f32_16x16x32_bf16 v[86:89], v[146:149], v[204:207], v[86:89]
	v_mfma_f32_16x16x32_bf16 v[82:85], v[154:157], v[204:207], v[82:85]
	s_setprio 0
	s_setprio 1
	v_mfma_f32_16x16x32_bf16 v[110:113], v[158:161], v[174:177], 0
	v_mfma_f32_16x16x32_bf16 v[106:109], v[166:169], v[174:177], 0
	v_mfma_f32_16x16x32_bf16 v[94:97], v[158:161], v[182:185], 0
	v_mfma_f32_16x16x32_bf16 v[90:93], v[166:169], v[182:185], 0
	v_mfma_f32_16x16x32_bf16 v[78:81], v[158:161], v[192:195], 0
	v_mfma_f32_16x16x32_bf16 v[74:77], v[166:169], v[192:195], 0
	v_mfma_f32_16x16x32_bf16 v[70:73], v[158:161], v[200:203], 0
	v_mfma_f32_16x16x32_bf16 v[66:69], v[166:169], v[200:203], 0
	v_mfma_f32_16x16x32_bf16 v[110:113], v[162:165], v[178:181], v[110:113]
	v_mfma_f32_16x16x32_bf16 v[106:109], v[170:173], v[178:181], v[106:109]
	v_mfma_f32_16x16x32_bf16 v[94:97], v[162:165], v[186:189], v[94:97]
	v_mfma_f32_16x16x32_bf16 v[90:93], v[170:173], v[186:189], v[90:93]
	v_mfma_f32_16x16x32_bf16 v[78:81], v[162:165], v[196:199], v[78:81]
	v_mfma_f32_16x16x32_bf16 v[74:77], v[170:173], v[196:199], v[74:77]
	v_mfma_f32_16x16x32_bf16 v[70:73], v[162:165], v[204:207], v[70:73]
	v_mfma_f32_16x16x32_bf16 v[66:69], v[170:173], v[204:207], v[66:69]
	s_setprio 0
	s_barrier
	s_add_i32 s93, vcc_lo, s49
	s_mov_b32 m0, s93
	ds_read_b128 v[174:177], v141 offset:16384
	ds_read_b128 v[178:181], v141 offset:17408
	ds_read_b128 v[182:185], v141 offset:18432
	ds_read_b128 v[186:189], v141 offset:19456
	ds_read_b128 v[192:195], v141 offset:20480
	ds_read_b128 v[196:199], v141 offset:21504
	ds_read_b128 v[200:203], v141 offset:22528
	ds_read_b128 v[204:207], v141 offset:23552
	global_load_lds_dwordx4 v0, s[44:45]
	s_add_i32 m0, s93, 0x2000
	s_add_u32 s100, s44, 0x40000
	s_addc_u32 s101, s45, 0
	s_add_i32 s85, s85, s49
	global_load_lds_dwordx4 v134, s[44:45]
	s_mov_b32 m0, s85
	s_nop 0
	global_load_lds_dwordx4 v0, s[100:101]
	s_add_i32 m0, s85, 0x2000
	s_nop 0
	global_load_lds_dwordx4 v134, s[100:101]
	s_mov_b32 m0, s9
	s_nop 0
	global_load_lds_dwordx4 v130, s[58:59]
	s_mov_b32 m0, s56
	s_nop 0
	global_load_lds_dwordx4 v132, s[58:59]
	s_waitcnt vmcnt(8)
	s_waitcnt lgkmcnt(0)
	s_barrier
	s_setprio 1
	s_waitcnt lgkmcnt(0)
	v_mfma_f32_16x16x32_bf16 v[62:65], v[142:145], v[174:177], 0
	v_mfma_f32_16x16x32_bf16 v[58:61], v[150:153], v[174:177], 0
	v_mfma_f32_16x16x32_bf16 v[54:57], v[142:145], v[182:185], 0
	v_mfma_f32_16x16x32_bf16 v[50:53], v[150:153], v[182:185], 0
	v_mfma_f32_16x16x32_bf16 v[38:41], v[142:145], v[192:195], 0
	v_mfma_f32_16x16x32_bf16 v[34:37], v[150:153], v[192:195], 0
	v_mfma_f32_16x16x32_bf16 v[22:25], v[142:145], v[200:203], 0
	v_mfma_f32_16x16x32_bf16 v[18:21], v[150:153], v[200:203], 0
	v_mfma_f32_16x16x32_bf16 v[62:65], v[146:149], v[178:181], v[62:65]
	v_mfma_f32_16x16x32_bf16 v[58:61], v[154:157], v[178:181], v[58:61]
	v_mfma_f32_16x16x32_bf16 v[54:57], v[146:149], v[186:189], v[54:57]
	v_mfma_f32_16x16x32_bf16 v[50:53], v[154:157], v[186:189], v[50:53]
	v_mfma_f32_16x16x32_bf16 v[38:41], v[146:149], v[196:199], v[38:41]
	v_mfma_f32_16x16x32_bf16 v[34:37], v[154:157], v[196:199], v[34:37]
	v_mfma_f32_16x16x32_bf16 v[22:25], v[146:149], v[204:207], v[22:25]
	v_mfma_f32_16x16x32_bf16 v[18:21], v[154:157], v[204:207], v[18:21]
	s_setprio 0
	s_setprio 1
	v_mfma_f32_16x16x32_bf16 v[46:49], v[158:161], v[174:177], 0
	v_mfma_f32_16x16x32_bf16 v[42:45], v[166:169], v[174:177], 0
	v_mfma_f32_16x16x32_bf16 v[30:33], v[158:161], v[182:185], 0
	v_mfma_f32_16x16x32_bf16 v[26:29], v[166:169], v[182:185], 0
	v_mfma_f32_16x16x32_bf16 v[14:17], v[158:161], v[192:195], 0
	v_mfma_f32_16x16x32_bf16 v[10:13], v[166:169], v[192:195], 0
	v_mfma_f32_16x16x32_bf16 v[6:9], v[158:161], v[200:203], 0
	v_mfma_f32_16x16x32_bf16 v[2:5], v[166:169], v[200:203], 0
	v_mfma_f32_16x16x32_bf16 v[46:49], v[162:165], v[178:181], v[46:49]
	v_mfma_f32_16x16x32_bf16 v[42:45], v[170:173], v[178:181], v[42:45]
	v_mfma_f32_16x16x32_bf16 v[30:33], v[162:165], v[186:189], v[30:33]
	v_mfma_f32_16x16x32_bf16 v[26:29], v[170:173], v[186:189], v[26:29]
	v_mfma_f32_16x16x32_bf16 v[14:17], v[162:165], v[196:199], v[14:17]
	v_mfma_f32_16x16x32_bf16 v[10:13], v[170:173], v[196:199], v[10:13]
	v_mfma_f32_16x16x32_bf16 v[6:9], v[162:165], v[204:207], v[6:9]
	v_mfma_f32_16x16x32_bf16 v[2:5], v[170:173], v[204:207], v[2:5]
	s_setprio 0
	s_barrier
	s_add_i32 s85, 0, 0x18000
	s_add_i32 s93, 0, 0x1c000
	v_add_u32_e32 v154, s85, v140
	v_add_u32_e32 v170, s93, v140
	ds_read_b128 v[142:145], v154
	ds_read_b128 v[146:149], v154 offset:1024
	ds_read_b128 v[150:153], v154 offset:2048
	ds_read_b128 v[154:157], v154 offset:3072
	ds_read_b128 v[158:161], v170
	ds_read_b128 v[162:165], v170 offset:1024
	ds_read_b128 v[166:169], v170 offset:2048
	ds_read_b128 v[170:173], v170 offset:3072
	s_add_u32 s58, s58, 0x40000
	s_addc_u32 s59, s59, 0
	s_mov_b32 m0, s57
	ds_read_b128 v[174:177], v141 offset:32768
	ds_read_b128 v[178:181], v141 offset:33792
	ds_read_b128 v[182:185], v141 offset:34816
	ds_read_b128 v[186:189], v141 offset:35840
	ds_read_b128 v[192:195], v141 offset:36864
	ds_read_b128 v[196:199], v141 offset:37888
	ds_read_b128 v[200:203], v141 offset:38912
	ds_read_b128 v[204:207], v141 offset:39936
	global_load_lds_dwordx4 v130, s[58:59]
	s_mov_b32 m0, s66
	s_nop 0
	global_load_lds_dwordx4 v132, s[58:59]
	s_waitcnt vmcnt(8)
	s_waitcnt lgkmcnt(0)
	s_barrier
	s_setprio 1
	s_waitcnt lgkmcnt(0)
	v_mfma_f32_16x16x32_bf16 v[126:129], v[142:145], v[174:177], v[126:129]
	v_mfma_f32_16x16x32_bf16 v[122:125], v[150:153], v[174:177], v[122:125]
	v_mfma_f32_16x16x32_bf16 v[118:121], v[142:145], v[182:185], v[118:121]
	v_mfma_f32_16x16x32_bf16 v[114:117], v[150:153], v[182:185], v[114:117]
	v_mfma_f32_16x16x32_bf16 v[102:105], v[142:145], v[192:195], v[102:105]
	v_mfma_f32_16x16x32_bf16 v[98:101], v[150:153], v[192:195], v[98:101]
	v_mfma_f32_16x16x32_bf16 v[86:89], v[142:145], v[200:203], v[86:89]
	v_mfma_f32_16x16x32_bf16 v[82:85], v[150:153], v[200:203], v[82:85]
	v_mfma_f32_16x16x32_bf16 v[126:129], v[146:149], v[178:181], v[126:129]
	v_mfma_f32_16x16x32_bf16 v[122:125], v[154:157], v[178:181], v[122:125]
	v_mfma_f32_16x16x32_bf16 v[118:121], v[146:149], v[186:189], v[118:121]
	v_mfma_f32_16x16x32_bf16 v[114:117], v[154:157], v[186:189], v[114:117]
	v_mfma_f32_16x16x32_bf16 v[102:105], v[146:149], v[196:199], v[102:105]
	v_mfma_f32_16x16x32_bf16 v[98:101], v[154:157], v[196:199], v[98:101]
	v_mfma_f32_16x16x32_bf16 v[86:89], v[146:149], v[204:207], v[86:89]
	v_mfma_f32_16x16x32_bf16 v[82:85], v[154:157], v[204:207], v[82:85]
	s_setprio 0
	s_setprio 1
	v_mfma_f32_16x16x32_bf16 v[110:113], v[158:161], v[174:177], v[110:113]
	v_mfma_f32_16x16x32_bf16 v[106:109], v[166:169], v[174:177], v[106:109]
	v_mfma_f32_16x16x32_bf16 v[94:97], v[158:161], v[182:185], v[94:97]
	v_mfma_f32_16x16x32_bf16 v[90:93], v[166:169], v[182:185], v[90:93]
	v_mfma_f32_16x16x32_bf16 v[78:81], v[158:161], v[192:195], v[78:81]
	v_mfma_f32_16x16x32_bf16 v[74:77], v[166:169], v[192:195], v[74:77]
	v_mfma_f32_16x16x32_bf16 v[70:73], v[158:161], v[200:203], v[70:73]
	v_mfma_f32_16x16x32_bf16 v[66:69], v[166:169], v[200:203], v[66:69]
	v_mfma_f32_16x16x32_bf16 v[110:113], v[162:165], v[178:181], v[110:113]
	v_mfma_f32_16x16x32_bf16 v[106:109], v[170:173], v[178:181], v[106:109]
	v_mfma_f32_16x16x32_bf16 v[94:97], v[162:165], v[186:189], v[94:97]
	v_mfma_f32_16x16x32_bf16 v[90:93], v[170:173], v[186:189], v[90:93]
	v_mfma_f32_16x16x32_bf16 v[78:81], v[162:165], v[196:199], v[78:81]
	v_mfma_f32_16x16x32_bf16 v[74:77], v[170:173], v[196:199], v[74:77]
	v_mfma_f32_16x16x32_bf16 v[70:73], v[162:165], v[204:207], v[70:73]
	v_mfma_f32_16x16x32_bf16 v[66:69], v[170:173], v[204:207], v[66:69]
	s_setprio 0
	s_barrier
	s_add_i32 m0, s85, s49
	s_add_u32 s100, s44, 0x80
	s_addc_u32 s101, s45, 0
	ds_read_b128 v[174:177], v141 offset:49152
	ds_read_b128 v[178:181], v141 offset:50176
	ds_read_b128 v[182:185], v141 offset:51200
	ds_read_b128 v[186:189], v141 offset:52224
	ds_read_b128 v[192:195], v141 offset:53248
	ds_read_b128 v[196:199], v141 offset:54272
	ds_read_b128 v[200:203], v141 offset:55296
	ds_read_b128 v[204:207], v141 offset:56320
	global_load_lds_dwordx4 v0, s[100:101]
	s_add_i32 m0, m0, 0x2000
	s_add_u32 s44, s44, 0x40080
	s_addc_u32 s45, s45, 0
	s_add_i32 s85, s93, s49
	global_load_lds_dwordx4 v134, s[100:101]
	s_mov_b32 m0, s85
	s_nop 0
	global_load_lds_dwordx4 v0, s[44:45]
	s_add_i32 m0, s85, 0x2000
	s_sub_u32 s100, s58, 0x3ff80
	s_subb_u32 s101, s59, 0
	global_load_lds_dwordx4 v134, s[44:45]
	s_mov_b32 m0, s71
	s_nop 0
	global_load_lds_dwordx4 v130, s[100:101]
	s_mov_b32 m0, s74
	s_nop 0
	global_load_lds_dwordx4 v132, s[100:101]
	s_waitcnt vmcnt(8)
	s_waitcnt lgkmcnt(0)
	s_barrier
	s_setprio 1
	s_waitcnt lgkmcnt(0)
	v_mfma_f32_16x16x32_bf16 v[62:65], v[142:145], v[174:177], v[62:65]
	v_mfma_f32_16x16x32_bf16 v[58:61], v[150:153], v[174:177], v[58:61]
	v_mfma_f32_16x16x32_bf16 v[54:57], v[142:145], v[182:185], v[54:57]
	v_mfma_f32_16x16x32_bf16 v[50:53], v[150:153], v[182:185], v[50:53]
	v_mfma_f32_16x16x32_bf16 v[38:41], v[142:145], v[192:195], v[38:41]
	v_mfma_f32_16x16x32_bf16 v[34:37], v[150:153], v[192:195], v[34:37]
	v_mfma_f32_16x16x32_bf16 v[22:25], v[142:145], v[200:203], v[22:25]
	v_mfma_f32_16x16x32_bf16 v[18:21], v[150:153], v[200:203], v[18:21]
	v_mfma_f32_16x16x32_bf16 v[62:65], v[146:149], v[178:181], v[62:65]
	v_mfma_f32_16x16x32_bf16 v[58:61], v[154:157], v[178:181], v[58:61]
	v_mfma_f32_16x16x32_bf16 v[54:57], v[146:149], v[186:189], v[54:57]
	v_mfma_f32_16x16x32_bf16 v[50:53], v[154:157], v[186:189], v[50:53]
	v_mfma_f32_16x16x32_bf16 v[38:41], v[146:149], v[196:199], v[38:41]
	v_mfma_f32_16x16x32_bf16 v[34:37], v[154:157], v[196:199], v[34:37]
	v_mfma_f32_16x16x32_bf16 v[22:25], v[146:149], v[204:207], v[22:25]
	v_mfma_f32_16x16x32_bf16 v[18:21], v[154:157], v[204:207], v[18:21]
	s_setprio 0
	s_setprio 1
	v_mfma_f32_16x16x32_bf16 v[46:49], v[158:161], v[174:177], v[46:49]
	v_mfma_f32_16x16x32_bf16 v[42:45], v[166:169], v[174:177], v[42:45]
	v_mfma_f32_16x16x32_bf16 v[30:33], v[158:161], v[182:185], v[30:33]
	v_mfma_f32_16x16x32_bf16 v[26:29], v[166:169], v[182:185], v[26:29]
	v_mfma_f32_16x16x32_bf16 v[14:17], v[158:161], v[192:195], v[14:17]
	v_mfma_f32_16x16x32_bf16 v[10:13], v[166:169], v[192:195], v[10:13]
	v_mfma_f32_16x16x32_bf16 v[6:9], v[158:161], v[200:203], v[6:9]
	v_mfma_f32_16x16x32_bf16 v[2:5], v[166:169], v[200:203], v[2:5]
	v_mfma_f32_16x16x32_bf16 v[46:49], v[162:165], v[178:181], v[46:49]
	v_mfma_f32_16x16x32_bf16 v[42:45], v[170:173], v[178:181], v[42:45]
	v_mfma_f32_16x16x32_bf16 v[30:33], v[162:165], v[186:189], v[30:33]
	v_mfma_f32_16x16x32_bf16 v[26:29], v[170:173], v[186:189], v[26:29]
	v_mfma_f32_16x16x32_bf16 v[14:17], v[162:165], v[196:199], v[14:17]
	v_mfma_f32_16x16x32_bf16 v[10:13], v[170:173], v[196:199], v[10:13]
	v_mfma_f32_16x16x32_bf16 v[6:9], v[162:165], v[204:207], v[6:9]
	v_mfma_f32_16x16x32_bf16 v[2:5], v[170:173], v[204:207], v[2:5]
	s_setprio 0
	s_barrier
	s_add_i32 s81, s81, 2
	s_add_u32 s38, s38, 0x100
	s_addc_u32 s39, s39, 0
	s_cmp_lt_u32 s81, 14

.LBB0_163:
	v_mov_b32_e32 v178, v191
	s_barrier
	s_mul_i32 s100, s30, 0xfe
	v_readfirstlane_b32 s101, v191
	s_lshr_b32 s101, s101, 6
	s_lshl_b32 s101, s101, 5
	s_add_i32 s100, s100, s101
	s_add_i32 s101, s100, 32
	s_add_i32 s6, s100, -1
	s_cmp_lt_i32 s100, 0x4000
	s_cselect_b32 s7, 12, 8
	s_ashr_i32 s6, s6, s7
	s_ashr_i32 s101, s101, s7
	s_sub_i32 s100, s101, s6
	v_and_b32_e32 v224, 15, v191
	s_lshl_b32 s9, s8, 7
	v_lshl_or_b32 v225, v224, 3, s9
	v_lshlrev_b32_e32 v226, 2, v225
	global_load_dwordx4 v[174:177], v226, s[12:13]
	global_load_dwordx4 v[182:185], v226, s[12:13] offset:16
	global_load_dwordx4 v[142:145], v226, s[16:17]
	global_load_dwordx4 v[146:149], v226, s[16:17] offset:16
	global_load_dwordx4 v[150:153], v226, s[18:19]
	global_load_dwordx4 v[154:157], v226, s[18:19] offset:16
	global_load_dwordx4 v[158:161], v226, s[20:21]
	global_load_dwordx4 v[162:165], v226, s[20:21] offset:16
	global_load_dwordx4 v[192:195], v226, s[22:23]
	global_load_dwordx4 v[196:199], v226, s[22:23] offset:16
	global_load_dwordx4 v[200:203], v226, s[24:25]
	global_load_dwordx4 v[204:207], v226, s[24:25] offset:16
	global_load_dwordx4 v[208:211], v226, s[14:15]
	global_load_dwordx4 v[212:215], v226, s[14:15] offset:16
	global_load_dwordx4 v[216:219], v226, s[26:27]
	global_load_dwordx4 v[220:223], v226, s[26:27] offset:16
	s_lshl_b32 s6, s67, 6
	v_and_b32_e32 v179, 15, v178
	v_or_b32_e32 v181, s70, v179
	s_movk_i32 s7, 0x220
	v_and_b32_e32 v180, 48, v178
	s_add_i32 s6, s6, 0
	v_mul_lo_u32 v181, v181, s7
	v_add3_u32 v180, s6, v180, v181
	v_cvt_pk_bf16_f32 v62, v62, v63
	v_cvt_pk_bf16_f32 v63, v64, v65
	v_cvt_pk_bf16_f32 v64, v58, v59
	v_add_u32_e32 v58, 0x11100, v180
	v_cvt_pk_bf16_f32 v46, v46, v47
	v_cvt_pk_bf16_f32 v47, v48, v49
	v_cvt_pk_bf16_f32 v48, v42, v43
	v_cvt_pk_bf16_f32 v49, v44, v45
	ds_write_b128 v58, v[46:49]
	v_add_u32_e32 v46, 0x13200, v180
	v_cvt_pk_bf16_f32 v42, v54, v55
	v_cvt_pk_bf16_f32 v43, v56, v57
	v_cvt_pk_bf16_f32 v44, v50, v51
	v_cvt_pk_bf16_f32 v45, v52, v53
	ds_write_b128 v46, v[42:45]
	v_add_u32_e32 v42, 0x13300, v180
	v_cvt_pk_bf16_f32 v30, v30, v31
	v_cvt_pk_bf16_f32 v31, v32, v33
	v_cvt_pk_bf16_f32 v32, v26, v27
	v_cvt_pk_bf16_f32 v33, v28, v29
	v_cvt_pk_bf16_f32 v94, v94, v95
	v_cvt_pk_bf16_f32 v95, v96, v97
	v_cvt_pk_bf16_f32 v96, v90, v91
	v_cvt_pk_bf16_f32 v97, v92, v93
	ds_write_b128 v42, v[30:33]
	v_add_u32_e32 v30, 0x15400, v180
	v_cvt_pk_bf16_f32 v26, v38, v39
	v_cvt_pk_bf16_f32 v27, v40, v41
	v_cvt_pk_bf16_f32 v28, v34, v35
	v_cvt_pk_bf16_f32 v29, v36, v37
	s_lshl_b32 s6, s8, 7
	ds_write_b128 v180, v[94:97] offset:8960
	ds_write_b128 v30, v[26:29]
	v_add_u32_e32 v26, 0x15500, v180
	v_cvt_pk_bf16_f32 v14, v14, v15
	v_cvt_pk_bf16_f32 v15, v16, v17
	v_cvt_pk_bf16_f32 v16, v10, v11
	v_cvt_pk_bf16_f32 v17, v12, v13
	v_lshl_or_b32 v94, v179, 3, s6
	ds_write_b128 v26, v[14:17]
	v_add_u32_e32 v14, 0x17600, v180
	v_cvt_pk_bf16_f32 v10, v22, v23
	v_cvt_pk_bf16_f32 v11, v24, v25
	v_cvt_pk_bf16_f32 v12, v18, v19
	v_cvt_pk_bf16_f32 v13, v20, v21
	v_ashrrev_i32_e32 v95, 31, v94
	v_cvt_pk_bf16_f32 v126, v126, v127
	v_cvt_pk_bf16_f32 v127, v128, v129
	v_cvt_pk_bf16_f32 v128, v122, v123
	v_cvt_pk_bf16_f32 v129, v124, v125
	v_cvt_pk_bf16_f32 v110, v110, v111
	v_cvt_pk_bf16_f32 v111, v112, v113
	v_cvt_pk_bf16_f32 v112, v106, v107
	v_cvt_pk_bf16_f32 v113, v108, v109
	v_cvt_pk_bf16_f32 v106, v118, v119
	v_cvt_pk_bf16_f32 v107, v120, v121
	v_cvt_pk_bf16_f32 v108, v114, v115
	v_cvt_pk_bf16_f32 v109, v116, v117
	v_cvt_pk_bf16_f32 v90, v102, v103
	v_cvt_pk_bf16_f32 v91, v104, v105
	v_cvt_pk_bf16_f32 v92, v98, v99
	v_cvt_pk_bf16_f32 v93, v100, v101
	v_cvt_pk_bf16_f32 v78, v78, v79
	v_cvt_pk_bf16_f32 v79, v80, v81
	v_cvt_pk_bf16_f32 v80, v74, v75
	v_cvt_pk_bf16_f32 v81, v76, v77
	v_cvt_pk_bf16_f32 v74, v86, v87
	v_cvt_pk_bf16_f32 v75, v88, v89
	v_cvt_pk_bf16_f32 v76, v82, v83
	v_cvt_pk_bf16_f32 v77, v84, v85
	v_cvt_pk_bf16_f32 v70, v70, v71
	v_cvt_pk_bf16_f32 v71, v72, v73
	v_cvt_pk_bf16_f32 v72, v66, v67
	v_cvt_pk_bf16_f32 v73, v68, v69
	v_add_u32_e32 v66, 0x11000, v180
	v_cvt_pk_bf16_f32 v65, v60, v61
	ds_write_b128 v14, v[10:13]
	v_add_u32_e32 v10, 0x17700, v180
	v_cvt_pk_bf16_f32 v6, v6, v7
	v_cvt_pk_bf16_f32 v7, v8, v9
	v_cvt_pk_bf16_f32 v8, v2, v3
	v_cvt_pk_bf16_f32 v9, v4, v5
	v_lshlrev_b64 v[22:23], 2, v[94:95]
	ds_write_b128 v180, v[126:129]
	ds_write_b128 v180, v[110:113] offset:256
	ds_write_b128 v180, v[106:109] offset:8704
	ds_write_b128 v180, v[90:93] offset:17408
	ds_write_b128 v180, v[78:81] offset:17664
	ds_write_b128 v180, v[74:77] offset:26112
	ds_write_b128 v180, v[70:73] offset:26368
	ds_write_b128 v66, v[62:65]
	ds_write_b128 v10, v[6:9]
	v_lshl_add_u64 v[2:3], s[12:13], 0, v[22:23]
	v_lshl_add_u64 v[6:7], s[16:17], 0, v[22:23]
	s_waitcnt lgkmcnt(0)
	s_waitcnt vmcnt(0) lgkmcnt(0)
	s_barrier
	v_and_b32_e32 v47, 15, v191
	v_lshrrev_b32_e32 v48, 4, v191
	s_lshl_b32 s6, s8, 7
	v_lshl_or_b32 v44, v47, 3, s6
	v_lshlrev_b32_e32 v49, 3, v48
	s_movk_i32 s44, 0x220
	s_movk_i32 s49, 0x4000
	v_mul_lo_u32 v54, v49, s44
	v_lshl_add_u32 v54, v47, 4, v54
	v_add_u32_e32 v49, 1, v49
	s_mul_i32 s9, s30, 0xfe
	s_add_i32 s9, s9, -1
	v_add_u32_e32 v45, s9, v49
	v_readlane_b32 s28, v255, 19
	s_movk_i32 s38, 0x1600
	v_mov_b64_e32 v[50:51], s[10:11]
	v_mad_i64_i32 v[50:51], s[6:7], v45, s38, v[50:51]
	v_lshlrev_b32_e32 v52, 1, v44
	v_mov_b32_e32 v53, 0
	v_lshl_add_u64 v[50:51], v[50:51], 0, v[52:53]
	s_mov_b32 s39, 0
	v_mov_b32_e32 v42, 0xbfb8aa3b
	ds_read_b128 v[114:117], v54 offset:0
	ds_read_b128 v[118:121], v54 offset:256
	ds_read_b128 v[122:125], v54 offset:544
	ds_read_b128 v[126:129], v54 offset:800
	s_waitcnt lgkmcnt(2)
	v_lshlrev_b32_e32 v66, 16, v114
	v_and_b32_e32 v67, 0xffff0000, v114
	v_lshlrev_b32_e32 v68, 16, v115
	v_and_b32_e32 v69, 0xffff0000, v115
	v_lshlrev_b32_e32 v70, 16, v116
	v_and_b32_e32 v71, 0xffff0000, v116
	v_lshlrev_b32_e32 v72, 16, v117
	v_and_b32_e32 v73, 0xffff0000, v117
	v_lshlrev_b32_e32 v74, 16, v118
	v_and_b32_e32 v75, 0xffff0000, v118
	v_lshlrev_b32_e32 v76, 16, v119
	v_and_b32_e32 v77, 0xffff0000, v119
	v_lshlrev_b32_e32 v78, 16, v120
	v_and_b32_e32 v79, 0xffff0000, v120
	v_lshlrev_b32_e32 v80, 16, v121
	v_and_b32_e32 v81, 0xffff0000, v121
	ds_read_b128 v[114:117], v54 offset:1088
	ds_read_b128 v[118:121], v54 offset:1344
	s_waitcnt lgkmcnt(2)
	v_lshlrev_b32_e32 v82, 16, v122
	v_and_b32_e32 v83, 0xffff0000, v122
	v_lshlrev_b32_e32 v84, 16, v123
	v_and_b32_e32 v85, 0xffff0000, v123
	v_lshlrev_b32_e32 v86, 16, v124
	v_and_b32_e32 v87, 0xffff0000, v124
	v_lshlrev_b32_e32 v88, 16, v125
	v_and_b32_e32 v89, 0xffff0000, v125
	v_lshlrev_b32_e32 v90, 16, v126
	v_and_b32_e32 v91, 0xffff0000, v126
	v_lshlrev_b32_e32 v92, 16, v127
	v_and_b32_e32 v93, 0xffff0000, v127
	v_lshlrev_b32_e32 v94, 16, v128
	v_and_b32_e32 v95, 0xffff0000, v128
	v_lshlrev_b32_e32 v96, 16, v129
	v_and_b32_e32 v97, 0xffff0000, v129
	s_waitcnt vmcnt(0)
	s_waitcnt lgkmcnt(0)
	v_lshlrev_b32_e32 v98, 16, v114
	v_and_b32_e32 v99, 0xffff0000, v114
	v_lshlrev_b32_e32 v100, 16, v115
	v_and_b32_e32 v101, 0xffff0000, v115
	v_lshlrev_b32_e32 v102, 16, v116
	v_and_b32_e32 v103, 0xffff0000, v116
	v_lshlrev_b32_e32 v104, 16, v117
	v_and_b32_e32 v105, 0xffff0000, v117
	v_lshlrev_b32_e32 v106, 16, v118
	v_and_b32_e32 v107, 0xffff0000, v118
	v_lshlrev_b32_e32 v108, 16, v119
	v_and_b32_e32 v109, 0xffff0000, v119
	v_lshlrev_b32_e32 v110, 16, v120
	v_and_b32_e32 v111, 0xffff0000, v120
	v_lshlrev_b32_e32 v112, 16, v121
	v_and_b32_e32 v113, 0xffff0000, v121
	ds_read_b128 v[122:125], v54 offset:1632
	ds_read_b128 v[126:129], v54 offset:1888
	s_movk_i32 s6, 255
	v_cmp_gt_i32_e32 vcc, s6, v49
	s_mov_b32 s6, s28
	v_cmp_gt_i32_e64 s[6:7], s6, v45
	s_and_b64 s[6:7], vcc, s[6:7]
	s_and_saveexec_b64 s[28:29], s[6:7]
	s_cbranch_execz .Luc_skip0
	s_mov_b64 s[78:79], 0
	s_cmp_eq_u32 s100, 0
	s_cbranch_scc1 .Luc_fast0
	v_add_u32_e32 v52, 0, v45
	v_mov_b32_e32 v53, 0xff
	v_cmp_gt_i32_e32 vcc, s49, v52
	v_mov_b32_e32 v46, 0xfff
	s_nop 0
	v_cndmask_b32_e32 v53, v53, v46, vcc
	v_and_b32_e32 v52, v52, v53
	v_cmp_ne_u32_e32 vcc, 0, v52
	v_cmp_ne_u32_e64 s[6:7], v52, v53
	s_mov_b64 s[78:79], 0
	s_and_b64 s[76:77], vcc, s[6:7]
	s_xor_b64 s[76:77], s[76:77], exec
	s_cbranch_scc0 .Luc_fast0
	v_cndmask_b32_e32 v66, 0, v66, vcc
	v_cndmask_b32_e32 v67, 0, v67, vcc
	v_cndmask_b32_e32 v68, 0, v68, vcc
	v_cndmask_b32_e32 v69, 0, v69, vcc
	v_cndmask_b32_e32 v70, 0, v70, vcc
	v_cndmask_b32_e32 v71, 0, v71, vcc
	v_cndmask_b32_e32 v72, 0, v72, vcc
	v_cndmask_b32_e32 v73, 0, v73, vcc
	v_cndmask_b32_e32 v74, 0, v74, vcc
	v_cndmask_b32_e32 v75, 0, v75, vcc
	v_cndmask_b32_e32 v76, 0, v76, vcc
	v_cndmask_b32_e32 v77, 0, v77, vcc
	v_cndmask_b32_e32 v78, 0, v78, vcc
	v_cndmask_b32_e32 v79, 0, v79, vcc
	v_cndmask_b32_e32 v80, 0, v80, vcc
	v_cndmask_b32_e32 v81, 0, v81, vcc
	v_mov_b64_e32 v[2:3], v[98:99]
	v_mov_b64_e32 v[4:5], v[100:101]
	v_mov_b64_e32 v[6:7], v[102:103]
	v_mov_b64_e32 v[8:9], v[104:105]
	v_mov_b64_e32 v[10:11], v[106:107]
	v_mov_b64_e32 v[12:13], v[108:109]
	v_mov_b64_e32 v[14:15], v[110:111]
	v_mov_b64_e32 v[16:17], v[112:113]
	v_cndmask_b32_e64 v98, 0, v98, s[6:7]
	v_cndmask_b32_e64 v99, 0, v99, s[6:7]
	v_cndmask_b32_e64 v100, 0, v100, s[6:7]
	v_cndmask_b32_e64 v101, 0, v101, s[6:7]
	v_cndmask_b32_e64 v102, 0, v102, s[6:7]
	v_cndmask_b32_e64 v103, 0, v103, s[6:7]
	v_cndmask_b32_e64 v104, 0, v104, s[6:7]
	v_cndmask_b32_e64 v105, 0, v105, s[6:7]
	v_cndmask_b32_e64 v106, 0, v106, s[6:7]
	v_cndmask_b32_e64 v107, 0, v107, s[6:7]
	v_cndmask_b32_e64 v108, 0, v108, s[6:7]
	v_cndmask_b32_e64 v109, 0, v109, s[6:7]
	v_cndmask_b32_e64 v110, 0, v110, s[6:7]
	v_cndmask_b32_e64 v111, 0, v111, s[6:7]
	v_cndmask_b32_e64 v112, 0, v112, s[6:7]
	v_cndmask_b32_e64 v113, 0, v113, s[6:7]
	s_mov_b64 s[78:79], -1
.Luc_fast0:
	v_pk_fma_f32 v[18:19], v[150:151], v[82:83], v[208:209]
	v_pk_fma_f32 v[26:27], v[158:159], v[90:91], v[216:217]
	v_pk_fma_f32 v[20:21], v[152:153], v[84:85], v[210:211]
	v_pk_fma_f32 v[28:29], v[160:161], v[92:93], v[218:219]
	v_pk_fma_f32 v[22:23], v[154:155], v[86:87], v[212:213]
	v_pk_fma_f32 v[30:31], v[162:163], v[94:95], v[220:221]
	v_pk_fma_f32 v[24:25], v[156:157], v[88:89], v[214:215]
	v_pk_fma_f32 v[32:33], v[164:165], v[96:97], v[222:223]
	v_pk_fma_f32 v[18:19], v[174:175], v[66:67], v[18:19]
	v_pk_fma_f32 v[26:27], v[142:143], v[74:75], v[26:27]
	v_pk_fma_f32 v[20:21], v[176:177], v[68:69], v[20:21]
	v_pk_fma_f32 v[28:29], v[144:145], v[76:77], v[28:29]
	v_pk_fma_f32 v[22:23], v[182:183], v[70:71], v[22:23]
	v_pk_fma_f32 v[30:31], v[146:147], v[78:79], v[30:31]
	v_pk_fma_f32 v[24:25], v[184:185], v[72:73], v[24:25]
	v_pk_fma_f32 v[32:33], v[148:149], v[80:81], v[32:33]
	v_pk_fma_f32 v[18:19], v[192:193], v[98:99], v[18:19]
	v_pk_fma_f32 v[26:27], v[200:201], v[106:107], v[26:27]
	v_pk_fma_f32 v[20:21], v[194:195], v[100:101], v[20:21]
	v_pk_fma_f32 v[28:29], v[202:203], v[108:109], v[28:29]
	v_pk_fma_f32 v[22:23], v[196:197], v[102:103], v[22:23]
	v_pk_fma_f32 v[30:31], v[204:205], v[110:111], v[30:31]
	v_pk_fma_f32 v[24:25], v[198:199], v[104:105], v[24:25]
	v_pk_fma_f32 v[32:33], v[206:207], v[112:113], v[32:33]
	v_pk_mul_f32 v[34:35], v[18:19], v[42:43] op_sel_hi:[1,0]
	v_pk_mul_f32 v[36:37], v[20:21], v[42:43] op_sel_hi:[1,0]
	v_pk_mul_f32 v[38:39], v[22:23], v[42:43] op_sel_hi:[1,0]
	v_pk_mul_f32 v[40:41], v[24:25], v[42:43] op_sel_hi:[1,0]
	v_exp_f32_e32 v34, v34
	v_exp_f32_e32 v35, v35
	v_exp_f32_e32 v36, v36
	v_exp_f32_e32 v37, v37
	v_exp_f32_e32 v38, v38
	v_exp_f32_e32 v39, v39
	v_exp_f32_e32 v40, v40
	v_exp_f32_e32 v41, v41
	v_pk_add_f32 v[34:35], v[34:35], 1.0 op_sel_hi:[1,0]
	v_pk_add_f32 v[36:37], v[36:37], 1.0 op_sel_hi:[1,0]
	v_pk_add_f32 v[38:39], v[38:39], 1.0 op_sel_hi:[1,0]
	v_pk_add_f32 v[40:41], v[40:41], 1.0 op_sel_hi:[1,0]
	v_rcp_f32_e32 v34, v34
	v_rcp_f32_e32 v35, v35
	v_rcp_f32_e32 v36, v36
	v_rcp_f32_e32 v37, v37
	v_rcp_f32_e32 v38, v38
	v_rcp_f32_e32 v39, v39
	v_rcp_f32_e32 v40, v40
	v_rcp_f32_e32 v41, v41
	v_pk_mul_f32 v[18:19], v[18:19], v[34:35]
	v_pk_mul_f32 v[20:21], v[20:21], v[36:37]
	v_pk_mul_f32 v[22:23], v[22:23], v[38:39]
	v_pk_mul_f32 v[24:25], v[24:25], v[40:41]
	v_pk_mul_f32 v[18:19], v[26:27], v[18:19]
	v_pk_mul_f32 v[20:21], v[28:29], v[20:21]
	v_pk_mul_f32 v[22:23], v[30:31], v[22:23]
	v_pk_mul_f32 v[24:25], v[32:33], v[24:25]
	v_cvt_pk_bf16_f32 v34, v18, v19
	v_cvt_pk_bf16_f32 v35, v20, v21
	v_cvt_pk_bf16_f32 v36, v22, v23
	v_cvt_pk_bf16_f32 v37, v24, v25
	global_store_dwordx4 v[50:51], v[34:37], off nt
	s_and_b64 vcc, exec, s[78:79]
	s_cbranch_vccz .Luc_skip0
	v_mov_b64_e32 v[98:99], v[2:3]
	v_mov_b64_e32 v[100:101], v[4:5]
	v_mov_b64_e32 v[102:103], v[6:7]
	v_mov_b64_e32 v[104:105], v[8:9]
	v_mov_b64_e32 v[106:107], v[10:11]
	v_mov_b64_e32 v[108:109], v[12:13]
	v_mov_b64_e32 v[110:111], v[14:15]
	v_mov_b64_e32 v[112:113], v[16:17]

.Luc_fast1:
	v_pk_fma_f32 v[18:19], v[150:151], v[98:99], v[208:209]
	v_pk_fma_f32 v[26:27], v[158:159], v[106:107], v[216:217]
	v_pk_fma_f32 v[20:21], v[152:153], v[100:101], v[210:211]
	v_pk_fma_f32 v[28:29], v[160:161], v[108:109], v[218:219]
	v_pk_fma_f32 v[22:23], v[154:155], v[102:103], v[212:213]
	v_pk_fma_f32 v[30:31], v[162:163], v[110:111], v[220:221]
	v_pk_fma_f32 v[24:25], v[156:157], v[104:105], v[214:215]
	v_pk_fma_f32 v[32:33], v[164:165], v[112:113], v[222:223]
	v_pk_fma_f32 v[18:19], v[174:175], v[82:83], v[18:19]
	v_pk_fma_f32 v[26:27], v[142:143], v[90:91], v[26:27]
	v_pk_fma_f32 v[20:21], v[176:177], v[84:85], v[20:21]
	v_pk_fma_f32 v[28:29], v[144:145], v[92:93], v[28:29]
	v_pk_fma_f32 v[22:23], v[182:183], v[86:87], v[22:23]
	v_pk_fma_f32 v[30:31], v[146:147], v[94:95], v[30:31]
	v_pk_fma_f32 v[24:25], v[184:185], v[88:89], v[24:25]
	v_pk_fma_f32 v[32:33], v[148:149], v[96:97], v[32:33]
	v_pk_fma_f32 v[18:19], v[192:193], v[66:67], v[18:19]
	v_pk_fma_f32 v[26:27], v[200:201], v[74:75], v[26:27]
	v_pk_fma_f32 v[20:21], v[194:195], v[68:69], v[20:21]
	v_pk_fma_f32 v[28:29], v[202:203], v[76:77], v[28:29]
	v_pk_fma_f32 v[22:23], v[196:197], v[70:71], v[22:23]
	v_pk_fma_f32 v[30:31], v[204:205], v[78:79], v[30:31]
	v_pk_fma_f32 v[24:25], v[198:199], v[72:73], v[24:25]
	v_pk_fma_f32 v[32:33], v[206:207], v[80:81], v[32:33]
	v_pk_mul_f32 v[34:35], v[18:19], v[42:43] op_sel_hi:[1,0]
	v_pk_mul_f32 v[36:37], v[20:21], v[42:43] op_sel_hi:[1,0]
	v_pk_mul_f32 v[38:39], v[22:23], v[42:43] op_sel_hi:[1,0]
	v_pk_mul_f32 v[40:41], v[24:25], v[42:43] op_sel_hi:[1,0]
	v_exp_f32_e32 v34, v34
	v_exp_f32_e32 v35, v35
	v_exp_f32_e32 v36, v36
	v_exp_f32_e32 v37, v37
	v_exp_f32_e32 v38, v38
	v_exp_f32_e32 v39, v39
	v_exp_f32_e32 v40, v40
	v_exp_f32_e32 v41, v41
	v_pk_add_f32 v[34:35], v[34:35], 1.0 op_sel_hi:[1,0]
	v_pk_add_f32 v[36:37], v[36:37], 1.0 op_sel_hi:[1,0]
	v_pk_add_f32 v[38:39], v[38:39], 1.0 op_sel_hi:[1,0]
	v_pk_add_f32 v[40:41], v[40:41], 1.0 op_sel_hi:[1,0]
	v_rcp_f32_e32 v34, v34
	v_rcp_f32_e32 v35, v35
	v_rcp_f32_e32 v36, v36
	v_rcp_f32_e32 v37, v37
	v_rcp_f32_e32 v38, v38
	v_rcp_f32_e32 v39, v39
	v_rcp_f32_e32 v40, v40
	v_rcp_f32_e32 v41, v41
	v_pk_mul_f32 v[18:19], v[18:19], v[34:35]
	v_pk_mul_f32 v[20:21], v[20:21], v[36:37]
	v_pk_mul_f32 v[22:23], v[22:23], v[38:39]
	v_pk_mul_f32 v[24:25], v[24:25], v[40:41]
	v_pk_mul_f32 v[18:19], v[26:27], v[18:19]
	v_pk_mul_f32 v[20:21], v[28:29], v[20:21]
	v_pk_mul_f32 v[22:23], v[30:31], v[22:23]
	v_pk_mul_f32 v[24:25], v[32:33], v[24:25]
	v_cvt_pk_bf16_f32 v34, v18, v19
	v_cvt_pk_bf16_f32 v35, v20, v21
	v_cvt_pk_bf16_f32 v36, v22, v23
	v_cvt_pk_bf16_f32 v37, v24, v25
	global_store_dwordx4 v[50:51], v[34:37], off nt
	s_and_b64 vcc, exec, s[78:79]
	s_cbranch_vccz .Luc_skip1
	v_mov_b64_e32 v[66:67], v[2:3]
	v_mov_b64_e32 v[68:69], v[4:5]
	v_mov_b64_e32 v[70:71], v[6:7]
	v_mov_b64_e32 v[72:73], v[8:9]
	v_mov_b64_e32 v[74:75], v[10:11]
	v_mov_b64_e32 v[76:77], v[12:13]
	v_mov_b64_e32 v[78:79], v[14:15]
	v_mov_b64_e32 v[80:81], v[16:17]

.Luc_fast2:
	v_pk_fma_f32 v[18:19], v[150:151], v[66:67], v[208:209]
	v_pk_fma_f32 v[26:27], v[158:159], v[74:75], v[216:217]
	v_pk_fma_f32 v[20:21], v[152:153], v[68:69], v[210:211]
	v_pk_fma_f32 v[28:29], v[160:161], v[76:77], v[218:219]
	v_pk_fma_f32 v[22:23], v[154:155], v[70:71], v[212:213]
	v_pk_fma_f32 v[30:31], v[162:163], v[78:79], v[220:221]
	v_pk_fma_f32 v[24:25], v[156:157], v[72:73], v[214:215]
	v_pk_fma_f32 v[32:33], v[164:165], v[80:81], v[222:223]
	v_pk_fma_f32 v[18:19], v[174:175], v[98:99], v[18:19]
	v_pk_fma_f32 v[26:27], v[142:143], v[106:107], v[26:27]
	v_pk_fma_f32 v[20:21], v[176:177], v[100:101], v[20:21]
	v_pk_fma_f32 v[28:29], v[144:145], v[108:109], v[28:29]
	v_pk_fma_f32 v[22:23], v[182:183], v[102:103], v[22:23]
	v_pk_fma_f32 v[30:31], v[146:147], v[110:111], v[30:31]
	v_pk_fma_f32 v[24:25], v[184:185], v[104:105], v[24:25]
	v_pk_fma_f32 v[32:33], v[148:149], v[112:113], v[32:33]
	v_pk_fma_f32 v[18:19], v[192:193], v[82:83], v[18:19]
	v_pk_fma_f32 v[26:27], v[200:201], v[90:91], v[26:27]
	v_pk_fma_f32 v[20:21], v[194:195], v[84:85], v[20:21]
	v_pk_fma_f32 v[28:29], v[202:203], v[92:93], v[28:29]
	v_pk_fma_f32 v[22:23], v[196:197], v[86:87], v[22:23]
	v_pk_fma_f32 v[30:31], v[204:205], v[94:95], v[30:31]
	v_pk_fma_f32 v[24:25], v[198:199], v[88:89], v[24:25]
	v_pk_fma_f32 v[32:33], v[206:207], v[96:97], v[32:33]
	v_pk_mul_f32 v[34:35], v[18:19], v[42:43] op_sel_hi:[1,0]
	v_pk_mul_f32 v[36:37], v[20:21], v[42:43] op_sel_hi:[1,0]
	v_pk_mul_f32 v[38:39], v[22:23], v[42:43] op_sel_hi:[1,0]
	v_pk_mul_f32 v[40:41], v[24:25], v[42:43] op_sel_hi:[1,0]
	v_exp_f32_e32 v34, v34
	v_exp_f32_e32 v35, v35
	v_exp_f32_e32 v36, v36
	v_exp_f32_e32 v37, v37
	v_exp_f32_e32 v38, v38
	v_exp_f32_e32 v39, v39
	v_exp_f32_e32 v40, v40
	v_exp_f32_e32 v41, v41
	v_pk_add_f32 v[34:35], v[34:35], 1.0 op_sel_hi:[1,0]
	v_pk_add_f32 v[36:37], v[36:37], 1.0 op_sel_hi:[1,0]
	v_pk_add_f32 v[38:39], v[38:39], 1.0 op_sel_hi:[1,0]
	v_pk_add_f32 v[40:41], v[40:41], 1.0 op_sel_hi:[1,0]
	v_rcp_f32_e32 v34, v34
	v_rcp_f32_e32 v35, v35
	v_rcp_f32_e32 v36, v36
	v_rcp_f32_e32 v37, v37
	v_rcp_f32_e32 v38, v38
	v_rcp_f32_e32 v39, v39
	v_rcp_f32_e32 v40, v40
	v_rcp_f32_e32 v41, v41
	v_pk_mul_f32 v[18:19], v[18:19], v[34:35]
	v_pk_mul_f32 v[20:21], v[20:21], v[36:37]
	v_pk_mul_f32 v[22:23], v[22:23], v[38:39]
	v_pk_mul_f32 v[24:25], v[24:25], v[40:41]
	v_pk_mul_f32 v[18:19], v[26:27], v[18:19]
	v_pk_mul_f32 v[20:21], v[28:29], v[20:21]
	v_pk_mul_f32 v[22:23], v[30:31], v[22:23]
	v_pk_mul_f32 v[24:25], v[32:33], v[24:25]
	v_cvt_pk_bf16_f32 v34, v18, v19
	v_cvt_pk_bf16_f32 v35, v20, v21
	v_cvt_pk_bf16_f32 v36, v22, v23
	v_cvt_pk_bf16_f32 v37, v24, v25
	global_store_dwordx4 v[50:51], v[34:37], off nt
	s_and_b64 vcc, exec, s[78:79]
	s_cbranch_vccz .Luc_skip2
	v_mov_b64_e32 v[82:83], v[2:3]
	v_mov_b64_e32 v[84:85], v[4:5]
	v_mov_b64_e32 v[86:87], v[6:7]
	v_mov_b64_e32 v[88:89], v[8:9]
	v_mov_b64_e32 v[90:91], v[10:11]
	v_mov_b64_e32 v[92:93], v[12:13]
	v_mov_b64_e32 v[94:95], v[14:15]
	v_mov_b64_e32 v[96:97], v[16:17]
